# g16 + P5 items distributed dynamically: per-launch-zeroed atomic counter + LDS broadcast instead of static it=bid+k*nblk (balances data-dependent selected-block work)
# speedup vs baseline: 1.0046x; 1.0046x over previous
; DI float sigmoidf_(float x) { return 1.0f / (1.0f + __expf(-x)); }
; DI void store4(u16* dst, f32x4 v) { uint2 w; w.x = cvtpk(v[0], v[1]); w.y = cvtpk(v[2], v[3]); *(uint2*)dst = w; }
; DI f32x4 load4bf(const u16* src) { uint2 w = *(const uint2*)src; return (f32x4){bflo(w.x), bfhi(w.x), bflo(w.y), bfhi(w.y)}; }
; DI void selwin_item(const Params& p, int it, unsigned char* smem, u16* y_out) {
;     ...
;   const u16* ma = (const u16*)(p.ws + OFF_MA); const u16* mbp = (const u16*)(p.ws + OFF_MB); const u16* ab = (const u16*)(p.ws + OFF_HBUF);
; #pragma unroll
;   for (int nt = 0; nt < 2; ++nt) {
;     const size_t t = tb0 + s0 + nt * 16 + lr;
; #pragma unroll
;     for (int dt = 0; dt < 4; ++dt) {
;       const size_t idx = t * 1024 + h * 64 + dt * 16 + lq * 4;
;       const f32x4 a = load4bf(ab + idx), mav = load4bf(ma + idx), mbv = load4bf(mbp + idx);
;       f32x4 y;
; #pragma unroll
;       for (int j = 0; j < 4; ++j) y[j] = sigmoidf_(mav[j]) * (a[j] + Ores[dt][nt][j]) + mbv[j];
;       { const int col = h * 64 + dt * 16 + lq * 4; store4(y_out + ((size_t)(col >> 5) * Tn + t) * 32 + (col & 31), y); }
;     }
;   }
; DI void phase5(const Params& p, int bid, int nblk, unsigned char* smem, u16* y_out) {
;   for (int it = bid; it < 8192; it += nblk) selwin_item(p, it, smem, y_out);
.LBB0_691:
	v_readfirstlane_b32 s98, v218
	s_cmp_lg_u32 s98, 0
	s_cbranch_scc1 .Ldyn5_skip_a
	s_mov_b64 s[100:101], exec
	s_mov_b64 exec, 1
	v_mov_b32_e32 v185, 0x3fb04000
	v_mov_b32_e32 v186, 1
	global_atomic_add v184, v185, v186, s[42:43] sc0
	s_mov_b64 exec, s[100:101]
.Ldyn5_skip_a:
	v_or_b32_e32 v136, v136, v151
	v_lshlrev_b64 v[0:1], 10, v[152:153]
	v_lshl_add_u64 v[0:1], v[0:1], 0, v[136:137]
	v_readlane_b32 s8, v245, 25
	v_lshlrev_b64 v[4:5], 1, v[0:1]
	v_readlane_b32 s9, v245, 26
	v_lshlrev_b64 v[2:3], 6, v[152:153]
	v_lshl_add_u64 v[6:7], s[16:17], 0, v[2:3]
	v_lshl_add_u64 v[0:1], s[8:9], 0, v[4:5]
	global_load_dwordx2 v[10:11], v[0:1], off
	v_lshl_add_u64 v[0:1], s[22:23], 0, v[4:5]
	global_load_dwordx2 v[12:13], v[0:1], off
	v_lshl_add_u64 v[0:1], s[2:3], 0, v[4:5]
	global_load_dwordx2 v[14:15], v[0:1], off
	v_lshlrev_b32_e32 v0, 1, v150
	v_ashrrev_i32_e32 v1, 31, v0
	v_lshlrev_b64 v[2:3], 22, v[0:1]
	v_pk_add_f32 v[16:17], v[160:161], v[78:79]
	v_pk_add_f32 v[18:19], v[162:163], v[76:77]
	v_lshlrev_b32_e32 v120, 1, v151
	v_lshl_add_u64 v[8:9], v[6:7], 0, v[2:3]
	v_or_b32_e32 v20, 32, v4
	v_mov_b32_e32 v21, v5
	v_lshl_add_u64 v[8:9], v[8:9], 0, v[120:121]
	v_lshl_add_u64 v[22:23], s[8:9], 0, v[20:21]
	v_or_b32_e32 v0, 1, v0
	s_waitcnt vmcnt(2)
	v_lshlrev_b32_e32 v24, 16, v10
	v_and_b32_e32 v25, 0xffff0000, v10
	s_waitcnt vmcnt(1)
	v_lshlrev_b32_e32 v1, 16, v12
	v_and_b32_e32 v26, 0xffff0000, v12
	v_lshlrev_b32_e32 v27, 16, v13
	v_mul_f32_e32 v1, 0xbfb8aa3b, v1
	v_mul_f32_e32 v29, 0xbfb8aa3b, v26
	v_and_b32_e32 v28, 0xffff0000, v13
	v_mul_f32_e32 v30, 0xbfb8aa3b, v27
	v_exp_f32_e32 v26, v1
	v_exp_f32_e32 v27, v29
	v_mul_f32_e32 v31, 0xbfb8aa3b, v28
	v_exp_f32_e32 v28, v30
	v_exp_f32_e32 v29, v31
	v_lshlrev_b32_e32 v10, 16, v11
	v_and_b32_e32 v11, 0xffff0000, v11
	v_pk_add_f32 v[10:11], v[16:17], v[10:11]
	v_pk_add_f32 v[16:17], v[26:27], 1.0 op_sel_hi:[1,0]
	v_pk_add_f32 v[18:19], v[18:19], v[24:25]
	v_pk_add_f32 v[24:25], v[28:29], 1.0 op_sel_hi:[1,0]
	s_mov_b64 vcc, s[0:1]
	v_rcp_f32_e32 v17, v17
	s_mov_b64 vcc, s[4:5]
	s_waitcnt vmcnt(0)
	v_lshlrev_b32_e32 v12, 16, v14
	v_and_b32_e32 v13, 0xffff0000, v14
	v_rcp_f32_e32 v16, v16
	s_mov_b64 vcc, s[6:7]
	v_pk_fma_f32 v[12:13], v[18:19], v[16:17], v[12:13]
	v_rcp_f32_e32 v17, v25
	v_lshlrev_b32_e32 v14, 16, v15
	v_and_b32_e32 v15, 0xffff0000, v15
	v_rcp_f32_e32 v16, v24
	s_nop 0
	v_pk_fma_f32 v[10:11], v[10:11], v[16:17], v[14:15]
	v_cvt_pk_bf16_f32 v12, v12, v13
	v_cvt_pk_bf16_f32 v13, v10, v11
	global_store_dwordx2 v[8:9], v[12:13], off
	v_lshl_add_u64 v[12:13], s[22:23], 0, v[20:21]
	global_load_dwordx2 v[12:13], v[12:13], off
	v_lshl_add_u64 v[14:15], s[2:3], 0, v[20:21]
	global_load_dwordx2 v[10:11], v[22:23], off
	v_pk_add_f32 v[16:17], v[154:155], v[74:75]
	global_load_dwordx2 v[14:15], v[14:15], off
	v_pk_add_f32 v[18:19], v[156:157], v[72:73]
	v_or_b32_e32 v20, 64, v4
	v_lshl_add_u64 v[22:23], s[8:9], 0, v[20:21]
	v_or_b32_e32 v4, 0x60, v4
	s_waitcnt vmcnt(2)
	v_lshlrev_b32_e32 v1, 16, v12
	v_and_b32_e32 v26, 0xffff0000, v12
	v_lshlrev_b32_e32 v27, 16, v13
	v_mul_f32_e32 v1, 0xbfb8aa3b, v1
	v_mul_f32_e32 v29, 0xbfb8aa3b, v26
	v_and_b32_e32 v28, 0xffff0000, v13
	v_mul_f32_e32 v30, 0xbfb8aa3b, v27
	v_exp_f32_e32 v26, v1
	v_exp_f32_e32 v27, v29
	v_mul_f32_e32 v31, 0xbfb8aa3b, v28
	v_exp_f32_e32 v28, v30
	v_exp_f32_e32 v29, v31
	s_waitcnt vmcnt(1)
	v_lshlrev_b32_e32 v24, 16, v10
	v_and_b32_e32 v25, 0xffff0000, v10
	v_lshlrev_b32_e32 v10, 16, v11
	v_and_b32_e32 v11, 0xffff0000, v11
	v_pk_add_f32 v[10:11], v[16:17], v[10:11]
	v_pk_add_f32 v[16:17], v[26:27], 1.0 op_sel_hi:[1,0]
	v_pk_add_f32 v[18:19], v[18:19], v[24:25]
	v_pk_add_f32 v[24:25], v[28:29], 1.0 op_sel_hi:[1,0]
	s_mov_b64 vcc, s[0:1]
	v_rcp_f32_e32 v17, v17
	s_mov_b64 vcc, s[4:5]
	s_waitcnt vmcnt(0)
	v_lshlrev_b32_e32 v12, 16, v14
	v_and_b32_e32 v13, 0xffff0000, v14
	v_rcp_f32_e32 v16, v16
	s_mov_b64 vcc, s[6:7]
	v_pk_fma_f32 v[12:13], v[18:19], v[16:17], v[12:13]
	v_rcp_f32_e32 v17, v25
	v_lshlrev_b32_e32 v14, 16, v15
	v_and_b32_e32 v15, 0xffff0000, v15
	v_rcp_f32_e32 v16, v24
	s_nop 0
	v_pk_fma_f32 v[10:11], v[10:11], v[16:17], v[14:15]
	v_cvt_pk_bf16_f32 v12, v12, v13
	v_cvt_pk_bf16_f32 v13, v10, v11
	global_store_dwordx2 v[8:9], v[12:13], off offset:32
	v_lshl_add_u64 v[10:11], s[22:23], 0, v[20:21]
	global_load_dwordx2 v[10:11], v[10:11], off
	v_lshl_add_u64 v[12:13], s[2:3], 0, v[20:21]
	global_load_dwordx2 v[8:9], v[22:23], off
	v_pk_add_f32 v[14:15], v[146:147], v[70:71]
	global_load_dwordx2 v[12:13], v[12:13], off
	v_pk_add_f32 v[16:17], v[148:149], v[68:69]
	v_ashrrev_i32_e32 v1, 31, v0
	v_lshlrev_b64 v[0:1], 22, v[0:1]
	v_lshl_add_u64 v[6:7], v[6:7], 0, v[0:1]
	v_lshl_add_u64 v[6:7], v[6:7], 0, v[120:121]
	v_lshl_add_u64 v[18:19], s[8:9], 0, v[4:5]
	s_waitcnt vmcnt(2)
	v_lshlrev_b32_e32 v22, 16, v10
	v_and_b32_e32 v23, 0xffff0000, v10
	v_mul_f32_e32 v22, 0xbfb8aa3b, v22
	v_mul_f32_e32 v23, 0xbfb8aa3b, v23
	v_lshlrev_b32_e32 v24, 16, v11
	v_and_b32_e32 v25, 0xffff0000, v11
	v_exp_f32_e32 v22, v22
	v_exp_f32_e32 v23, v23
	v_mul_f32_e32 v24, 0xbfb8aa3b, v24
	v_mul_f32_e32 v25, 0xbfb8aa3b, v25
	v_exp_f32_e32 v24, v24
	v_exp_f32_e32 v25, v25
	s_waitcnt vmcnt(1)
	v_lshlrev_b32_e32 v20, 16, v8
	v_and_b32_e32 v21, 0xffff0000, v8
	v_lshlrev_b32_e32 v8, 16, v9
	v_and_b32_e32 v9, 0xffff0000, v9
	v_pk_add_f32 v[8:9], v[14:15], v[8:9]
	v_pk_add_f32 v[14:15], v[22:23], 1.0 op_sel_hi:[1,0]
	v_pk_add_f32 v[16:17], v[16:17], v[20:21]
	v_pk_add_f32 v[20:21], v[24:25], 1.0 op_sel_hi:[1,0]
	s_mov_b64 vcc, s[0:1]
	v_rcp_f32_e32 v15, v15
	s_mov_b64 vcc, s[4:5]
	s_waitcnt vmcnt(0)
; DI float sigmoidf_(float x) { return 1.0f / (1.0f + __expf(-x)); }
; DI void store4(u16* dst, f32x4 v) { uint2 w; w.x = cvtpk(v[0], v[1]); w.y = cvtpk(v[2], v[3]); *(uint2*)dst = w; }
; DI f32x4 load4bf(const u16* src) { uint2 w = *(const uint2*)src; return (f32x4){bflo(w.x), bfhi(w.x), bflo(w.y), bfhi(w.y)}; }
; DI void selwin_item(const Params& p, int it, unsigned char* smem, u16* y_out) {
;     ...
;   const u16* ma = (const u16*)(p.ws + OFF_MA); const u16* mbp = (const u16*)(p.ws + OFF_MB); const u16* ab = (const u16*)(p.ws + OFF_HBUF);
; #pragma unroll
;   for (int nt = 0; nt < 2; ++nt) {
;     const size_t t = tb0 + s0 + nt * 16 + lr;
; #pragma unroll
;     for (int dt = 0; dt < 4; ++dt) {
;       const size_t idx = t * 1024 + h * 64 + dt * 16 + lq * 4;
;       const f32x4 a = load4bf(ab + idx), mav = load4bf(ma + idx), mbv = load4bf(mbp + idx);
;       f32x4 y;
; #pragma unroll
;       for (int j = 0; j < 4; ++j) y[j] = sigmoidf_(mav[j]) * (a[j] + Ores[dt][nt][j]) + mbv[j];
;       { const int col = h * 64 + dt * 16 + lq * 4; store4(y_out + ((size_t)(col >> 5) * Tn + t) * 32 + (col & 31), y); }
;     }
;   }
	v_lshlrev_b32_e32 v10, 16, v12
	v_and_b32_e32 v11, 0xffff0000, v12
	v_rcp_f32_e32 v14, v14
	s_mov_b64 vcc, s[6:7]
	v_pk_fma_f32 v[10:11], v[16:17], v[14:15], v[10:11]
	v_lshlrev_b32_e32 v12, 16, v13
	v_and_b32_e32 v13, 0xffff0000, v13
	v_rcp_f32_e32 v15, v21
	v_rcp_f32_e32 v14, v20
	s_nop 0
	v_pk_fma_f32 v[8:9], v[8:9], v[14:15], v[12:13]
	v_cvt_pk_bf16_f32 v10, v10, v11
	v_cvt_pk_bf16_f32 v11, v8, v9
	global_store_dwordx2 v[6:7], v[10:11], off
	v_lshl_add_u64 v[10:11], s[22:23], 0, v[4:5]
	global_load_dwordx2 v[10:11], v[10:11], off
	v_lshl_add_u64 v[4:5], s[2:3], 0, v[4:5]
	global_load_dwordx2 v[8:9], v[18:19], off
	global_load_dwordx2 v[12:13], v[4:5], off
	v_pk_add_f32 v[14:15], v[142:143], v[66:67]
	v_pk_add_f32 v[16:17], v[144:145], v[64:65]
	v_lshlrev_b64 v[4:5], 10, v[130:131]
	v_lshl_add_u64 v[4:5], v[4:5], 0, v[136:137]
	v_lshlrev_b64 v[4:5], 1, v[4:5]
	v_lshl_add_u64 v[18:19], s[8:9], 0, v[4:5]
	s_waitcnt vmcnt(2)
	v_lshlrev_b32_e32 v22, 16, v10
	v_and_b32_e32 v23, 0xffff0000, v10
	v_mul_f32_e32 v22, 0xbfb8aa3b, v22
	v_mul_f32_e32 v23, 0xbfb8aa3b, v23
	v_lshlrev_b32_e32 v24, 16, v11
	v_and_b32_e32 v25, 0xffff0000, v11
	v_exp_f32_e32 v22, v22
	v_exp_f32_e32 v23, v23
	v_mul_f32_e32 v24, 0xbfb8aa3b, v24
	v_mul_f32_e32 v25, 0xbfb8aa3b, v25
	v_exp_f32_e32 v24, v24
	v_exp_f32_e32 v25, v25
	s_waitcnt vmcnt(1)
	v_lshlrev_b32_e32 v20, 16, v8
	v_and_b32_e32 v21, 0xffff0000, v8
	v_lshlrev_b32_e32 v8, 16, v9
	v_and_b32_e32 v9, 0xffff0000, v9
	v_pk_add_f32 v[8:9], v[14:15], v[8:9]
	v_pk_add_f32 v[14:15], v[22:23], 1.0 op_sel_hi:[1,0]
	v_pk_add_f32 v[16:17], v[16:17], v[20:21]
	v_pk_add_f32 v[20:21], v[24:25], 1.0 op_sel_hi:[1,0]
	s_mov_b64 vcc, s[0:1]
	v_rcp_f32_e32 v15, v15
	s_mov_b64 vcc, s[4:5]
	s_waitcnt vmcnt(0)
	v_lshlrev_b32_e32 v10, 16, v12
	v_and_b32_e32 v11, 0xffff0000, v12
	v_rcp_f32_e32 v14, v14
	s_mov_b64 vcc, s[6:7]
	v_pk_fma_f32 v[10:11], v[16:17], v[14:15], v[10:11]
	v_lshlrev_b32_e32 v12, 16, v13
	v_and_b32_e32 v13, 0xffff0000, v13
	v_rcp_f32_e32 v15, v21
	v_rcp_f32_e32 v14, v20
	s_nop 0
	v_pk_fma_f32 v[8:9], v[8:9], v[14:15], v[12:13]
	v_cvt_pk_bf16_f32 v10, v10, v11
	v_cvt_pk_bf16_f32 v11, v8, v9
	global_store_dwordx2 v[6:7], v[10:11], off offset:32
	v_lshl_add_u64 v[6:7], s[22:23], 0, v[4:5]
	global_load_dwordx2 v[10:11], v[6:7], off
	global_load_dwordx2 v[8:9], v[18:19], off
	v_lshl_add_u64 v[6:7], s[2:3], 0, v[4:5]
	global_load_dwordx2 v[12:13], v[6:7], off
	v_pk_add_f32 v[14:15], v[138:139], v[62:63]
	v_pk_add_f32 v[16:17], v[140:141], v[60:61]
	v_lshlrev_b64 v[6:7], 6, v[130:131]
	v_lshl_add_u64 v[6:7], s[16:17], 0, v[6:7]
	v_lshl_add_u64 v[2:3], v[6:7], 0, v[2:3]
	v_or_b32_e32 v18, 32, v4
	v_mov_b32_e32 v19, v5
	v_lshl_add_u64 v[2:3], v[2:3], 0, v[120:121]
	v_lshl_add_u64 v[20:21], s[8:9], 0, v[18:19]
	v_lshl_add_u64 v[0:1], v[6:7], 0, v[0:1]
	v_lshl_add_u64 v[0:1], v[0:1], 0, v[120:121]
	s_waitcnt vmcnt(2)
	v_lshlrev_b32_e32 v24, 16, v10
	v_and_b32_e32 v25, 0xffff0000, v10
	v_mul_f32_e32 v24, 0xbfb8aa3b, v24
	v_mul_f32_e32 v25, 0xbfb8aa3b, v25
	v_lshlrev_b32_e32 v26, 16, v11
	v_and_b32_e32 v27, 0xffff0000, v11
	v_exp_f32_e32 v24, v24
	v_exp_f32_e32 v25, v25
	v_mul_f32_e32 v26, 0xbfb8aa3b, v26
	v_mul_f32_e32 v27, 0xbfb8aa3b, v27
	v_exp_f32_e32 v26, v26
	v_exp_f32_e32 v27, v27
	s_waitcnt vmcnt(1)
	v_lshlrev_b32_e32 v22, 16, v8
	v_and_b32_e32 v23, 0xffff0000, v8
	v_lshlrev_b32_e32 v8, 16, v9
	v_and_b32_e32 v9, 0xffff0000, v9
	v_pk_add_f32 v[8:9], v[14:15], v[8:9]
	v_pk_add_f32 v[14:15], v[24:25], 1.0 op_sel_hi:[1,0]
	v_pk_add_f32 v[16:17], v[16:17], v[22:23]
	v_pk_add_f32 v[22:23], v[26:27], 1.0 op_sel_hi:[1,0]
	s_mov_b64 vcc, s[0:1]
	v_rcp_f32_e32 v15, v15
	s_mov_b64 vcc, s[4:5]
	s_waitcnt vmcnt(0)
	v_lshlrev_b32_e32 v10, 16, v12
	v_and_b32_e32 v11, 0xffff0000, v12
	v_rcp_f32_e32 v14, v14
	s_mov_b64 vcc, s[6:7]
	v_pk_fma_f32 v[10:11], v[16:17], v[14:15], v[10:11]
	v_lshlrev_b32_e32 v12, 16, v13
	v_and_b32_e32 v13, 0xffff0000, v13
	v_rcp_f32_e32 v15, v23
	v_rcp_f32_e32 v14, v22
	s_nop 0
	v_pk_fma_f32 v[8:9], v[8:9], v[14:15], v[12:13]
	v_cvt_pk_bf16_f32 v10, v10, v11
	v_cvt_pk_bf16_f32 v11, v8, v9
	global_store_dwordx2 v[2:3], v[10:11], off
	v_lshl_add_u64 v[10:11], s[22:23], 0, v[18:19]
	global_load_dwordx2 v[10:11], v[10:11], off
	v_lshl_add_u64 v[12:13], s[2:3], 0, v[18:19]
	global_load_dwordx2 v[8:9], v[20:21], off
	v_pk_add_f32 v[14:15], v[132:133], v[58:59]
	global_load_dwordx2 v[12:13], v[12:13], off
	v_pk_add_f32 v[16:17], v[134:135], v[56:57]
	v_or_b32_e32 v18, 64, v4
	v_lshl_add_u64 v[20:21], s[8:9], 0, v[18:19]
	v_or_b32_e32 v4, 0x60, v4
	v_lshl_add_u64 v[6:7], s[8:9], 0, v[4:5]
	s_waitcnt vmcnt(2)
; DI float sigmoidf_(float x) { return 1.0f / (1.0f + __expf(-x)); }
; DI void store4(u16* dst, f32x4 v) { uint2 w; w.x = cvtpk(v[0], v[1]); w.y = cvtpk(v[2], v[3]); *(uint2*)dst = w; }
; DI f32x4 load4bf(const u16* src) { uint2 w = *(const uint2*)src; return (f32x4){bflo(w.x), bfhi(w.x), bflo(w.y), bfhi(w.y)}; }
; DI void selwin_item(const Params& p, int it, unsigned char* smem, u16* y_out) {
;     ...
;   const u16* ma = (const u16*)(p.ws + OFF_MA); const u16* mbp = (const u16*)(p.ws + OFF_MB); const u16* ab = (const u16*)(p.ws + OFF_HBUF);
; #pragma unroll
;   for (int nt = 0; nt < 2; ++nt) {
;     const size_t t = tb0 + s0 + nt * 16 + lr;
; #pragma unroll
;     for (int dt = 0; dt < 4; ++dt) {
;       const size_t idx = t * 1024 + h * 64 + dt * 16 + lq * 4;
;       const f32x4 a = load4bf(ab + idx), mav = load4bf(ma + idx), mbv = load4bf(mbp + idx);
;       f32x4 y;
; #pragma unroll
;       for (int j = 0; j < 4; ++j) y[j] = sigmoidf_(mav[j]) * (a[j] + Ores[dt][nt][j]) + mbv[j];
;       { const int col = h * 64 + dt * 16 + lq * 4; store4(y_out + ((size_t)(col >> 5) * Tn + t) * 32 + (col & 31), y); }
;     }
;   }
; DI void phase5(const Params& p, int bid, int nblk, unsigned char* smem, u16* y_out) {
;   for (int it = bid; it < 8192; it += nblk) selwin_item(p, it, smem, y_out);
	v_lshlrev_b32_e32 v24, 16, v10
	v_and_b32_e32 v25, 0xffff0000, v10
	v_mul_f32_e32 v24, 0xbfb8aa3b, v24
	v_mul_f32_e32 v25, 0xbfb8aa3b, v25
	v_lshlrev_b32_e32 v26, 16, v11
	v_and_b32_e32 v27, 0xffff0000, v11
	v_exp_f32_e32 v24, v24
	v_exp_f32_e32 v25, v25
	v_mul_f32_e32 v26, 0xbfb8aa3b, v26
	v_mul_f32_e32 v27, 0xbfb8aa3b, v27
	v_exp_f32_e32 v26, v26
	v_exp_f32_e32 v27, v27
	s_waitcnt vmcnt(1)
	v_lshlrev_b32_e32 v22, 16, v8
	v_and_b32_e32 v23, 0xffff0000, v8
	v_lshlrev_b32_e32 v8, 16, v9
	v_and_b32_e32 v9, 0xffff0000, v9
	v_pk_add_f32 v[8:9], v[14:15], v[8:9]
	v_pk_add_f32 v[14:15], v[24:25], 1.0 op_sel_hi:[1,0]
	v_pk_add_f32 v[16:17], v[16:17], v[22:23]
	v_pk_add_f32 v[22:23], v[26:27], 1.0 op_sel_hi:[1,0]
	s_mov_b64 vcc, s[0:1]
	v_rcp_f32_e32 v15, v15
	s_mov_b64 vcc, s[4:5]
	s_waitcnt vmcnt(0)
	v_lshlrev_b32_e32 v10, 16, v12
	v_and_b32_e32 v11, 0xffff0000, v12
	v_rcp_f32_e32 v14, v14
	s_mov_b64 vcc, s[6:7]
	v_pk_fma_f32 v[10:11], v[16:17], v[14:15], v[10:11]
	v_lshlrev_b32_e32 v12, 16, v13
	v_and_b32_e32 v13, 0xffff0000, v13
	v_rcp_f32_e32 v15, v23
	v_rcp_f32_e32 v14, v22
	s_nop 0
	v_pk_fma_f32 v[8:9], v[8:9], v[14:15], v[12:13]
	v_cvt_pk_bf16_f32 v10, v10, v11
	v_cvt_pk_bf16_f32 v11, v8, v9
	global_store_dwordx2 v[2:3], v[10:11], off offset:32
	v_lshl_add_u64 v[8:9], s[22:23], 0, v[18:19]
	global_load_dwordx2 v[8:9], v[8:9], off
	v_lshl_add_u64 v[10:11], s[2:3], 0, v[18:19]
	global_load_dwordx2 v[2:3], v[20:21], off
	v_pk_add_f32 v[12:13], v[126:127], v[54:55]
	global_load_dwordx2 v[10:11], v[10:11], off
	v_pk_add_f32 v[14:15], v[128:129], v[52:53]
	s_waitcnt vmcnt(2)
	v_lshlrev_b32_e32 v18, 16, v8
	v_and_b32_e32 v19, 0xffff0000, v8
	v_mul_f32_e32 v18, 0xbfb8aa3b, v18
	v_mul_f32_e32 v19, 0xbfb8aa3b, v19
	v_lshlrev_b32_e32 v20, 16, v9
	v_and_b32_e32 v21, 0xffff0000, v9
	v_exp_f32_e32 v18, v18
	v_exp_f32_e32 v19, v19
	v_mul_f32_e32 v20, 0xbfb8aa3b, v20
	v_mul_f32_e32 v21, 0xbfb8aa3b, v21
	v_exp_f32_e32 v20, v20
	v_exp_f32_e32 v21, v21
	s_waitcnt vmcnt(1)
	v_lshlrev_b32_e32 v16, 16, v2
	v_and_b32_e32 v17, 0xffff0000, v2
	v_lshlrev_b32_e32 v2, 16, v3
	v_and_b32_e32 v3, 0xffff0000, v3
	v_pk_add_f32 v[2:3], v[12:13], v[2:3]
	v_pk_add_f32 v[12:13], v[18:19], 1.0 op_sel_hi:[1,0]
	v_pk_add_f32 v[14:15], v[14:15], v[16:17]
	v_pk_add_f32 v[16:17], v[20:21], 1.0 op_sel_hi:[1,0]
	s_mov_b64 vcc, s[0:1]
	v_rcp_f32_e32 v13, v13
	s_mov_b64 vcc, s[4:5]
	s_waitcnt vmcnt(0)
	v_lshlrev_b32_e32 v8, 16, v10
	v_and_b32_e32 v9, 0xffff0000, v10
	v_rcp_f32_e32 v12, v12
	s_mov_b64 vcc, s[6:7]
	v_pk_fma_f32 v[8:9], v[14:15], v[12:13], v[8:9]
	v_lshlrev_b32_e32 v10, 16, v11
	v_and_b32_e32 v11, 0xffff0000, v11
	v_rcp_f32_e32 v13, v17
	v_rcp_f32_e32 v12, v16
	s_nop 0
	v_pk_fma_f32 v[2:3], v[2:3], v[12:13], v[10:11]
	v_cvt_pk_bf16_f32 v8, v8, v9
	v_cvt_pk_bf16_f32 v9, v2, v3
	global_store_dwordx2 v[0:1], v[8:9], off
	global_load_dwordx2 v[2:3], v[6:7], off
	v_lshl_add_u64 v[6:7], s[22:23], 0, v[4:5]
	global_load_dwordx2 v[6:7], v[6:7], off
	v_lshl_add_u64 v[4:5], s[2:3], 0, v[4:5]
	global_load_dwordx2 v[4:5], v[4:5], off
	v_pk_add_f32 v[8:9], v[122:123], v[50:51]
	v_pk_add_f32 v[10:11], v[124:125], v[48:49]
	s_waitcnt vmcnt(2)
	v_lshlrev_b32_e32 v12, 16, v2
	v_and_b32_e32 v13, 0xffff0000, v2
	s_waitcnt vmcnt(1)
	v_lshlrev_b32_e32 v14, 16, v6
	v_and_b32_e32 v15, 0xffff0000, v6
	v_mul_f32_e32 v14, 0xbfb8aa3b, v14
	v_mul_f32_e32 v15, 0xbfb8aa3b, v15
	v_lshlrev_b32_e32 v16, 16, v7
	v_and_b32_e32 v17, 0xffff0000, v7
	v_exp_f32_e32 v14, v14
	v_exp_f32_e32 v15, v15
	v_mul_f32_e32 v16, 0xbfb8aa3b, v16
	v_mul_f32_e32 v17, 0xbfb8aa3b, v17
	v_exp_f32_e32 v16, v16
	v_exp_f32_e32 v17, v17
	v_lshlrev_b32_e32 v2, 16, v3
	v_and_b32_e32 v3, 0xffff0000, v3
	v_pk_add_f32 v[2:3], v[8:9], v[2:3]
	v_pk_add_f32 v[8:9], v[14:15], 1.0 op_sel_hi:[1,0]
	v_pk_add_f32 v[10:11], v[10:11], v[12:13]
	v_pk_add_f32 v[12:13], v[16:17], 1.0 op_sel_hi:[1,0]
	s_mov_b64 vcc, s[0:1]
	v_rcp_f32_e32 v9, v9
	s_mov_b64 vcc, s[4:5]
	s_waitcnt vmcnt(0)
	v_lshlrev_b32_e32 v6, 16, v4
	v_and_b32_e32 v7, 0xffff0000, v4
	v_rcp_f32_e32 v8, v8
	s_mov_b64 vcc, s[6:7]
	v_pk_fma_f32 v[6:7], v[10:11], v[8:9], v[6:7]
	v_lshlrev_b32_e32 v4, 16, v5
	v_and_b32_e32 v5, 0xffff0000, v5
	v_rcp_f32_e32 v9, v13
	v_rcp_f32_e32 v8, v12
	s_nop 0
	v_pk_fma_f32 v[2:3], v[2:3], v[8:9], v[4:5]
	v_cvt_pk_bf16_f32 v6, v6, v7
	v_cvt_pk_bf16_f32 v7, v2, v3
	global_store_dwordx2 v[0:1], v[6:7], off offset:32
	v_mov_b32_e32 v187, 0x5a00
	v_readfirstlane_b32 s98, v218
	s_cmp_lg_u32 s98, 0
	s_cbranch_scc1 .Ldyn5_skip_b
	s_waitcnt vmcnt(8)
	s_mov_b64 s[100:101], exec
	s_mov_b64 exec, 1
	ds_write_b32 v187, v184
	s_waitcnt lgkmcnt(0)
	s_mov_b64 exec, s[100:101]
.Ldyn5_skip_b:
	s_barrier
	ds_read_b32 v184, v187
	s_waitcnt lgkmcnt(0)
	v_readfirstlane_b32 s58, v184
	s_add_i32 s58, s58, s92
	s_cmpk_lt_i32 s58, 0x2000
	s_cbranch_scc0 .LBB0_754
